# hoist serialized Xin loads within (ai,m) groups + ssq loads in EpiXF false and true
# baseline (speedup 1.0000x reference)
;     __device__ __forceinline__ void operator()(f32x4 (&acc)[2][2][4][2], const Unit& u, int wr, int wc, int fr, int fq) const {
;     ...
;             for (int m = 0; m < 4; ++m) { const int row = row0 + ai * HALF + m * 16; const size_t off = (size_t)row * 2048 + col0; float ss = 0.f;
; #pragma unroll
;                 for (int bj = 0; bj < 2; ++bj)
; #pragma unroll
;                     for (int n = 0; n < 2; ++n) { const f32x4 xo = *(const f32x4*)(Xin + off + bj * HALF + n * 16) + acc[ai][bj][m][n]; acc[ai][bj][m][n] = xo;
;                         if (!FINAL) *(f32x4*)(X + off + bj * HALF + n * 16) = xo;
;                         ss += (xo[0] * xo[0] + xo[1] * xo[1]) + (xo[2] * xo[2] + xo[3] * xo[3]); }
;                 ss += __shfl_xor(ss, 16); ss += __shfl_xor(ss, 32);
;                 if (fq == 0) atomicAdd(ssq + row, ss); }
.LBB0_913:
	v_lshl_add_u32 v154, s13, 8, v178
	v_lshl_or_b32 v156, s34, 8, v180
	v_ashrrev_i32_e32 v155, 31, v154
	v_ashrrev_i32_e32 v157, 31, v156
	v_lshlrev_b64 v[152:153], 11, v[154:155]
	v_lshl_add_u64 v[152:153], v[152:153], 0, v[156:157]
	v_lshlrev_b64 v[152:153], 2, v[152:153]
	v_lshl_add_u64 v[162:163], s[14:15], 0, v[152:153]
	global_load_dwordx4 v[158:161], v[162:163], off
	global_load_dwordx4 v[196:199], v[162:163], off offset:64
	global_load_dwordx4 v[200:203], v[162:163], off offset:512
	global_load_dwordx4 v[204:207], v[162:163], off offset:576
	v_lshl_add_u64 v[152:153], s[58:59], 0, v[152:153]
	s_waitcnt vmcnt(3)
	v_pk_add_f32 v[76:77], v[76:77], v[160:161]
	v_pk_add_f32 v[74:75], v[74:75], v[158:159]
	global_store_dwordx4 v[152:153], v[74:77], off
	v_mul_f32_e32 v164, v77, v77
	v_fmac_f32_e32 v164, v76, v76
	s_waitcnt vmcnt(3)
	v_pk_add_f32 v[80:81], v[80:81], v[198:199]
	v_pk_add_f32 v[78:79], v[78:79], v[196:197]
	global_store_dwordx4 v[152:153], v[78:81], off offset:64
	v_mul_f32_e32 v165, v81, v81
	v_fmac_f32_e32 v165, v80, v80
	s_waitcnt vmcnt(3)
	v_pk_add_f32 v[84:85], v[84:85], v[202:203]
	v_pk_add_f32 v[82:83], v[82:83], v[200:201]
	global_store_dwordx4 v[152:153], v[82:85], off offset:512
	v_and_b32_e32 v163, 64, v241
	v_xor_b32_e32 v162, 16, v241
	v_add_u32_e32 v163, 64, v163
	v_cmp_lt_i32_e32 vcc, v162, v163
	s_waitcnt vmcnt(3)
	v_pk_add_f32 v[96:97], v[96:97], v[206:207]
	v_cndmask_b32_e32 v162, v241, v162, vcc
	v_lshlrev_b32_e32 v182, 2, v162
	v_mul_f32_e32 v162, v75, v75
	v_fmac_f32_e32 v162, v74, v74
	v_add_f32_e32 v162, v162, v164
	v_mul_f32_e32 v164, v79, v79
	v_fmac_f32_e32 v164, v78, v78
	v_add_f32_e32 v164, v164, v165
	v_add_f32_e32 v162, v162, v164
	v_mul_f32_e32 v164, v83, v83
	v_mul_f32_e32 v165, v85, v85
	v_pk_add_f32 v[94:95], v[94:95], v[204:205]
	v_fmac_f32_e32 v164, v82, v82
	v_fmac_f32_e32 v165, v84, v84
	v_mul_f32_e32 v158, v95, v95
	v_mul_f32_e32 v159, v97, v97
	v_add_f32_e32 v164, v164, v165
	v_fmac_f32_e32 v158, v94, v94
	v_fmac_f32_e32 v159, v96, v96
	v_add_f32_e32 v162, v162, v164
	v_add_f32_e32 v158, v158, v159
	v_add_f32_e32 v158, v162, v158
	ds_bpermute_b32 v159, v182, v158
	v_xor_b32_e32 v160, 32, v241
	v_cmp_lt_i32_e32 vcc, v160, v163
	global_store_dwordx4 v[152:153], v[94:97], off offset:576
	v_lshl_add_u64 v[152:153], v[154:155], 2, s[16:17]
	v_cndmask_b32_e32 v160, v241, v160, vcc
	v_lshlrev_b32_e32 v183, 2, v160
	s_waitcnt lgkmcnt(0)
	v_add_f32_e32 v158, v158, v159
	ds_bpermute_b32 v159, v183, v158
	s_and_saveexec_b64 s[0:1], s[4:5]
	s_mov_b32 s81, 0x2d400000
	s_cbranch_execz .LBB0_915
	s_waitcnt lgkmcnt(0)
	v_add_f32_e32 v158, v158, v159
	global_atomic_add_f32 v[152:153], v158, off
.LBB0_915:
	s_or_b64 exec, exec, s[0:1]
	v_or_b32_e32 v158, 16, v154
	s_waitcnt lgkmcnt(0)
	v_ashrrev_i32_e32 v159, 31, v158
	v_lshlrev_b64 v[160:161], 11, v[158:159]
	v_lshl_add_u64 v[160:161], v[160:161], 0, v[156:157]
	v_lshlrev_b64 v[164:165], 2, v[160:161]
	v_lshl_add_u64 v[166:167], s[14:15], 0, v[164:165]
	global_load_dwordx4 v[160:163], v[166:167], off
	global_load_dwordx4 v[196:199], v[166:167], off offset:64
	global_load_dwordx4 v[200:203], v[166:167], off offset:512
	global_load_dwordx4 v[204:207], v[166:167], off offset:576
	v_lshl_add_u64 v[164:165], s[58:59], 0, v[164:165]
	s_waitcnt vmcnt(3)
	v_pk_add_f32 v[104:105], v[104:105], v[162:163]
	v_pk_add_f32 v[102:103], v[102:103], v[160:161]
	global_store_dwordx4 v[164:165], v[102:105], off
	s_waitcnt vmcnt(3)
	v_pk_add_f32 v[108:109], v[108:109], v[198:199]
	v_pk_add_f32 v[106:107], v[106:107], v[196:197]
	global_store_dwordx4 v[164:165], v[106:109], off offset:64
	v_mul_f32_e32 v168, v109, v109
	v_fmac_f32_e32 v168, v108, v108
	s_waitcnt vmcnt(3)
	v_pk_add_f32 v[112:113], v[112:113], v[202:203]
	v_pk_add_f32 v[110:111], v[110:111], v[200:201]
	global_store_dwordx4 v[164:165], v[110:113], off offset:512
	v_mul_f32_e32 v166, v103, v103
	v_mul_f32_e32 v167, v105, v105
	v_fmac_f32_e32 v166, v102, v102
	v_fmac_f32_e32 v167, v104, v104
	v_add_f32_e32 v166, v166, v167
	v_mul_f32_e32 v167, v107, v107
	v_fmac_f32_e32 v167, v106, v106
	v_add_f32_e32 v167, v167, v168
	v_add_f32_e32 v166, v166, v167
	v_mul_f32_e32 v167, v111, v111
	v_mul_f32_e32 v168, v113, v113
	v_fmac_f32_e32 v167, v110, v110
	v_fmac_f32_e32 v168, v112, v112
	v_add_f32_e32 v167, v167, v168
	v_add_f32_e32 v166, v166, v167
	s_waitcnt vmcnt(3)
	v_pk_add_f32 v[120:121], v[120:121], v[206:207]
	v_pk_add_f32 v[118:119], v[118:119], v[204:205]
	v_mul_f32_e32 v161, v121, v121
	v_mul_f32_e32 v160, v119, v119
	v_fmac_f32_e32 v160, v118, v118
	v_fmac_f32_e32 v161, v120, v120
	v_add_f32_e32 v160, v160, v161
	v_add_f32_e32 v160, v166, v160
	ds_bpermute_b32 v161, v182, v160
	v_lshl_add_u64 v[162:163], v[158:159], 2, s[16:17]
	global_store_dwordx4 v[164:165], v[118:121], off offset:576
	s_waitcnt lgkmcnt(0)
	v_add_f32_e32 v160, v160, v161
	ds_bpermute_b32 v161, v183, v160
	s_and_saveexec_b64 s[0:1], s[4:5]
	s_cbranch_execz .LBB0_917
	s_waitcnt lgkmcnt(0)
	v_add_f32_e32 v160, v160, v161
	global_atomic_add_f32 v[162:163], v160, off
;     __device__ __forceinline__ void operator()(f32x4 (&acc)[2][2][4][2], const Unit& u, int wr, int wc, int fr, int fq) const {
;     ...
;             for (int m = 0; m < 4; ++m) { const int row = row0 + ai * HALF + m * 16; const size_t off = (size_t)row * 2048 + col0; float ss = 0.f;
; #pragma unroll
;                 for (int bj = 0; bj < 2; ++bj)
; #pragma unroll
;                     for (int n = 0; n < 2; ++n) { const f32x4 xo = *(const f32x4*)(Xin + off + bj * HALF + n * 16) + acc[ai][bj][m][n]; acc[ai][bj][m][n] = xo;
;                         if (!FINAL) *(f32x4*)(X + off + bj * HALF + n * 16) = xo;
;                         ss += (xo[0] * xo[0] + xo[1] * xo[1]) + (xo[2] * xo[2] + xo[3] * xo[3]); }
;                 ss += __shfl_xor(ss, 16); ss += __shfl_xor(ss, 32);
;                 if (fq == 0) atomicAdd(ssq + row, ss); }
.LBB0_917:
	s_or_b64 exec, exec, s[0:1]
	v_or_b32_e32 v160, 32, v154
	s_waitcnt lgkmcnt(0)
	v_ashrrev_i32_e32 v161, 31, v160
	v_lshlrev_b64 v[164:165], 11, v[160:161]
	v_lshl_add_u64 v[164:165], v[164:165], 0, v[156:157]
	v_lshlrev_b64 v[168:169], 2, v[164:165]
	v_lshl_add_u64 v[170:171], s[14:15], 0, v[168:169]
	global_load_dwordx4 v[164:167], v[170:171], off
	global_load_dwordx4 v[196:199], v[170:171], off offset:64
	global_load_dwordx4 v[200:203], v[170:171], off offset:512
	global_load_dwordx4 v[204:207], v[170:171], off offset:576
	v_lshl_add_u64 v[168:169], s[58:59], 0, v[168:169]
	s_waitcnt vmcnt(3)
	v_pk_add_f32 v[124:125], v[124:125], v[166:167]
	v_pk_add_f32 v[122:123], v[122:123], v[164:165]
	global_store_dwordx4 v[168:169], v[122:125], off
	s_waitcnt vmcnt(3)
	v_pk_add_f32 v[146:147], v[146:147], v[198:199]
	v_pk_add_f32 v[144:145], v[144:145], v[196:197]
	global_store_dwordx4 v[168:169], v[144:147], off offset:64
	v_mul_f32_e32 v172, v147, v147
	v_fmac_f32_e32 v172, v146, v146
	s_waitcnt vmcnt(3)
	v_pk_add_f32 v[116:117], v[116:117], v[202:203]
	v_pk_add_f32 v[114:115], v[114:115], v[200:201]
	global_store_dwordx4 v[168:169], v[114:117], off offset:512
	v_mul_f32_e32 v170, v123, v123
	v_mul_f32_e32 v171, v125, v125
	v_fmac_f32_e32 v170, v122, v122
	v_fmac_f32_e32 v171, v124, v124
	v_add_f32_e32 v170, v170, v171
	v_mul_f32_e32 v171, v145, v145
	v_fmac_f32_e32 v171, v144, v144
	v_add_f32_e32 v171, v171, v172
	v_add_f32_e32 v170, v170, v171
	v_mul_f32_e32 v171, v115, v115
	v_mul_f32_e32 v172, v117, v117
	v_fmac_f32_e32 v171, v114, v114
	v_fmac_f32_e32 v172, v116, v116
	v_add_f32_e32 v171, v171, v172
	v_add_f32_e32 v170, v170, v171
	s_waitcnt vmcnt(3)
	v_pk_add_f32 v[100:101], v[100:101], v[206:207]
	v_pk_add_f32 v[98:99], v[98:99], v[204:205]
	v_mul_f32_e32 v165, v101, v101
	v_mul_f32_e32 v164, v99, v99
	v_fmac_f32_e32 v164, v98, v98
	v_fmac_f32_e32 v165, v100, v100
	v_add_f32_e32 v164, v164, v165
	v_add_f32_e32 v164, v170, v164
	ds_bpermute_b32 v165, v182, v164
	v_lshl_add_u64 v[166:167], v[160:161], 2, s[16:17]
	global_store_dwordx4 v[168:169], v[98:101], off offset:576
	s_waitcnt lgkmcnt(0)
	v_add_f32_e32 v164, v164, v165
	ds_bpermute_b32 v165, v183, v164
	s_and_saveexec_b64 s[0:1], s[4:5]
	s_mov_b32 s91, 0xca00000
	s_cbranch_execz .LBB0_919
	s_waitcnt lgkmcnt(0)
	v_add_f32_e32 v164, v164, v165
	global_atomic_add_f32 v[166:167], v164, off
.LBB0_919:
	s_or_b64 exec, exec, s[0:1]
	v_or_b32_e32 v164, 48, v154
	s_waitcnt lgkmcnt(0)
	v_ashrrev_i32_e32 v165, 31, v164
	v_lshlrev_b64 v[168:169], 11, v[164:165]
	v_lshl_add_u64 v[168:169], v[168:169], 0, v[156:157]
	v_lshlrev_b64 v[172:173], 2, v[168:169]
	v_lshl_add_u64 v[174:175], s[14:15], 0, v[172:173]
	global_load_dwordx4 v[168:171], v[174:175], off
	global_load_dwordx4 v[196:199], v[174:175], off offset:64
	global_load_dwordx4 v[200:203], v[174:175], off offset:512
	global_load_dwordx4 v[204:207], v[174:175], off offset:576
	v_lshl_add_u64 v[172:173], s[58:59], 0, v[172:173]
	s_waitcnt vmcnt(3)
	v_pk_add_f32 v[92:93], v[92:93], v[170:171]
	v_pk_add_f32 v[90:91], v[90:91], v[168:169]
	global_store_dwordx4 v[172:173], v[90:93], off
	s_waitcnt vmcnt(3)
	v_pk_add_f32 v[88:89], v[88:89], v[198:199]
	v_pk_add_f32 v[86:87], v[86:87], v[196:197]
	global_store_dwordx4 v[172:173], v[86:89], off offset:64
	v_mul_f32_e32 v176, v89, v89
	v_fmac_f32_e32 v176, v88, v88
	s_waitcnt vmcnt(3)
	v_pk_add_f32 v[72:73], v[72:73], v[202:203]
	v_pk_add_f32 v[70:71], v[70:71], v[200:201]
	global_store_dwordx4 v[172:173], v[70:73], off offset:512
	v_mul_f32_e32 v174, v91, v91
	v_mul_f32_e32 v175, v93, v93
	v_fmac_f32_e32 v174, v90, v90
	v_fmac_f32_e32 v175, v92, v92
	v_add_f32_e32 v174, v174, v175
	v_mul_f32_e32 v175, v87, v87
	v_fmac_f32_e32 v175, v86, v86
	v_add_f32_e32 v175, v175, v176
	v_add_f32_e32 v174, v174, v175
	v_mul_f32_e32 v175, v71, v71
	v_mul_f32_e32 v176, v73, v73
	v_fmac_f32_e32 v175, v70, v70
	v_fmac_f32_e32 v176, v72, v72
	v_add_f32_e32 v175, v175, v176
	v_add_f32_e32 v174, v174, v175
	s_waitcnt vmcnt(3)
	v_pk_add_f32 v[68:69], v[68:69], v[206:207]
	v_pk_add_f32 v[66:67], v[66:67], v[204:205]
	v_mul_f32_e32 v169, v69, v69
	v_mul_f32_e32 v168, v67, v67
	v_fmac_f32_e32 v168, v66, v66
	v_fmac_f32_e32 v169, v68, v68
	v_add_f32_e32 v168, v168, v169
	v_add_f32_e32 v168, v174, v168
	ds_bpermute_b32 v169, v182, v168
	v_lshl_add_u64 v[170:171], v[164:165], 2, s[16:17]
	global_store_dwordx4 v[172:173], v[66:69], off offset:576
	s_waitcnt lgkmcnt(0)
	v_add_f32_e32 v168, v168, v169
	ds_bpermute_b32 v169, v183, v168
	s_and_saveexec_b64 s[0:1], s[4:5]
	s_cbranch_execz .LBB0_921
	s_waitcnt lgkmcnt(0)
	v_add_f32_e32 v168, v168, v169
	global_atomic_add_f32 v[170:171], v168, off
;     __device__ __forceinline__ void operator()(f32x4 (&acc)[2][2][4][2], const Unit& u, int wr, int wc, int fr, int fq) const {
;     ...
;             for (int m = 0; m < 4; ++m) { const int row = row0 + ai * HALF + m * 16; const size_t off = (size_t)row * 2048 + col0; float ss = 0.f;
; #pragma unroll
;                 for (int bj = 0; bj < 2; ++bj)
; #pragma unroll
;                     for (int n = 0; n < 2; ++n) { const f32x4 xo = *(const f32x4*)(Xin + off + bj * HALF + n * 16) + acc[ai][bj][m][n]; acc[ai][bj][m][n] = xo;
;                         if (!FINAL) *(f32x4*)(X + off + bj * HALF + n * 16) = xo;
;                         ss += (xo[0] * xo[0] + xo[1] * xo[1]) + (xo[2] * xo[2] + xo[3] * xo[3]); }
;                 ss += __shfl_xor(ss, 16); ss += __shfl_xor(ss, 32);
;                 if (fq == 0) atomicAdd(ssq + row, ss); }
.LBB0_921:
	s_or_b64 exec, exec, s[0:1]
	v_add_u32_e32 v168, 0x80, v154
	s_waitcnt lgkmcnt(0)
	v_ashrrev_i32_e32 v169, 31, v168
	v_lshlrev_b64 v[172:173], 11, v[168:169]
	v_lshl_add_u64 v[172:173], v[172:173], 0, v[156:157]
	v_lshlrev_b64 v[176:177], 2, v[172:173]
	v_lshl_add_u64 v[184:185], s[14:15], 0, v[176:177]
	global_load_dwordx4 v[172:175], v[184:185], off
	global_load_dwordx4 v[196:199], v[184:185], off offset:64
	global_load_dwordx4 v[200:203], v[184:185], off offset:512
	global_load_dwordx4 v[204:207], v[184:185], off offset:576
	v_lshl_add_u64 v[176:177], s[58:59], 0, v[176:177]
	s_waitcnt vmcnt(3)
	v_pk_add_f32 v[64:65], v[64:65], v[174:175]
	v_pk_add_f32 v[62:63], v[62:63], v[172:173]
	global_store_dwordx4 v[176:177], v[62:65], off
	s_waitcnt vmcnt(3)
	v_pk_add_f32 v[60:61], v[60:61], v[198:199]
	v_pk_add_f32 v[58:59], v[58:59], v[196:197]
	global_store_dwordx4 v[176:177], v[58:61], off offset:64
	v_mul_f32_e32 v186, v61, v61
	v_fmac_f32_e32 v186, v60, v60
	s_waitcnt vmcnt(3)
	v_pk_add_f32 v[56:57], v[56:57], v[202:203]
	v_pk_add_f32 v[54:55], v[54:55], v[200:201]
	global_store_dwordx4 v[176:177], v[54:57], off offset:512
	v_mul_f32_e32 v184, v63, v63
	v_mul_f32_e32 v185, v65, v65
	v_fmac_f32_e32 v184, v62, v62
	v_fmac_f32_e32 v185, v64, v64
	v_add_f32_e32 v184, v184, v185
	v_mul_f32_e32 v185, v59, v59
	v_fmac_f32_e32 v185, v58, v58
	v_add_f32_e32 v185, v185, v186
	v_add_f32_e32 v184, v184, v185
	v_mul_f32_e32 v185, v55, v55
	v_mul_f32_e32 v186, v57, v57
	v_fmac_f32_e32 v185, v54, v54
	v_fmac_f32_e32 v186, v56, v56
	v_add_f32_e32 v185, v185, v186
	v_add_f32_e32 v184, v184, v185
	s_waitcnt vmcnt(3)
	v_pk_add_f32 v[52:53], v[52:53], v[206:207]
	v_pk_add_f32 v[50:51], v[50:51], v[204:205]
	v_mul_f32_e32 v173, v53, v53
	v_mul_f32_e32 v172, v51, v51
	v_fmac_f32_e32 v172, v50, v50
	v_fmac_f32_e32 v173, v52, v52
	v_add_f32_e32 v172, v172, v173
	v_add_f32_e32 v172, v184, v172
	ds_bpermute_b32 v173, v182, v172
	global_store_dwordx4 v[176:177], v[50:53], off offset:576
	s_waitcnt lgkmcnt(0)
	v_add_f32_e32 v172, v172, v173
	ds_bpermute_b32 v173, v183, v172
	s_and_saveexec_b64 s[0:1], s[4:5]
	s_cbranch_execz .LBB0_923
	v_lshl_add_u64 v[174:175], v[168:169], 2, s[16:17]
	s_waitcnt lgkmcnt(0)
	v_add_f32_e32 v172, v172, v173
	global_atomic_add_f32 v[174:175], v172, off
.LBB0_923:
	s_or_b64 exec, exec, s[0:1]
	v_add_u32_e32 v172, 0x90, v154
	s_waitcnt lgkmcnt(0)
	v_ashrrev_i32_e32 v173, 31, v172
	v_lshlrev_b64 v[174:175], 11, v[172:173]
	v_lshl_add_u64 v[174:175], v[174:175], 0, v[156:157]
	v_lshlrev_b64 v[184:185], 2, v[174:175]
	v_lshl_add_u64 v[186:187], s[14:15], 0, v[184:185]
	global_load_dwordx4 v[174:177], v[186:187], off
	global_load_dwordx4 v[196:199], v[186:187], off offset:64
	global_load_dwordx4 v[200:203], v[186:187], off offset:512
	global_load_dwordx4 v[204:207], v[186:187], off offset:576
	v_lshl_add_u64 v[184:185], s[58:59], 0, v[184:185]
	s_waitcnt vmcnt(3)
	v_pk_add_f32 v[48:49], v[48:49], v[176:177]
	v_pk_add_f32 v[46:47], v[46:47], v[174:175]
	global_store_dwordx4 v[184:185], v[46:49], off
	s_waitcnt vmcnt(3)
	v_pk_add_f32 v[44:45], v[44:45], v[198:199]
	v_pk_add_f32 v[42:43], v[42:43], v[196:197]
	global_store_dwordx4 v[184:185], v[42:45], off offset:64
	v_mul_f32_e32 v188, v45, v45
	v_fmac_f32_e32 v188, v44, v44
	s_waitcnt vmcnt(3)
	v_pk_add_f32 v[40:41], v[40:41], v[202:203]
	v_pk_add_f32 v[38:39], v[38:39], v[200:201]
	global_store_dwordx4 v[184:185], v[38:41], off offset:512
	v_mul_f32_e32 v186, v47, v47
	v_mul_f32_e32 v187, v49, v49
	v_fmac_f32_e32 v186, v46, v46
	v_fmac_f32_e32 v187, v48, v48
	v_add_f32_e32 v186, v186, v187
	v_mul_f32_e32 v187, v43, v43
	v_fmac_f32_e32 v187, v42, v42
	v_add_f32_e32 v187, v187, v188
	v_add_f32_e32 v186, v186, v187
	v_mul_f32_e32 v187, v39, v39
	v_mul_f32_e32 v188, v41, v41
	v_fmac_f32_e32 v187, v38, v38
	v_fmac_f32_e32 v188, v40, v40
	v_add_f32_e32 v187, v187, v188
	v_add_f32_e32 v186, v186, v187
	s_waitcnt vmcnt(3)
	v_pk_add_f32 v[36:37], v[36:37], v[206:207]
	v_pk_add_f32 v[34:35], v[34:35], v[204:205]
	v_mul_f32_e32 v175, v37, v37
	v_mul_f32_e32 v174, v35, v35
	v_fmac_f32_e32 v174, v34, v34
	v_fmac_f32_e32 v175, v36, v36
	v_add_f32_e32 v174, v174, v175
	v_add_f32_e32 v174, v186, v174
	ds_bpermute_b32 v175, v182, v174
	global_store_dwordx4 v[184:185], v[34:37], off offset:576
	s_waitcnt lgkmcnt(0)
	v_add_f32_e32 v174, v174, v175
	ds_bpermute_b32 v175, v183, v174
	s_and_saveexec_b64 s[0:1], s[4:5]
	s_cbranch_execz .LBB0_925
	v_lshl_add_u64 v[176:177], v[172:173], 2, s[16:17]
	s_waitcnt lgkmcnt(0)
	v_add_f32_e32 v174, v174, v175
	global_atomic_add_f32 v[176:177], v174, off
;     __device__ __forceinline__ void operator()(f32x4 (&acc)[2][2][4][2], const Unit& u, int wr, int wc, int fr, int fq) const {
;     ...
;             for (int m = 0; m < 4; ++m) { const int row = row0 + ai * HALF + m * 16; const size_t off = (size_t)row * 2048 + col0; float ss = 0.f;
; #pragma unroll
;                 for (int bj = 0; bj < 2; ++bj)
; #pragma unroll
;                     for (int n = 0; n < 2; ++n) { const f32x4 xo = *(const f32x4*)(Xin + off + bj * HALF + n * 16) + acc[ai][bj][m][n]; acc[ai][bj][m][n] = xo;
;                         if (!FINAL) *(f32x4*)(X + off + bj * HALF + n * 16) = xo;
;                         ss += (xo[0] * xo[0] + xo[1] * xo[1]) + (xo[2] * xo[2] + xo[3] * xo[3]); }
;                 ss += __shfl_xor(ss, 16); ss += __shfl_xor(ss, 32);
;                 if (fq == 0) atomicAdd(ssq + row, ss); }
.LBB0_925:
	s_or_b64 exec, exec, s[0:1]
	v_add_u32_e32 v174, 0xa0, v154
	s_waitcnt lgkmcnt(0)
	v_ashrrev_i32_e32 v175, 31, v174
	v_lshlrev_b64 v[176:177], 11, v[174:175]
	v_lshl_add_u64 v[176:177], v[176:177], 0, v[156:157]
	v_lshlrev_b64 v[176:177], 2, v[176:177]
	v_lshl_add_u64 v[188:189], s[14:15], 0, v[176:177]
	global_load_dwordx4 v[184:187], v[188:189], off
	global_load_dwordx4 v[196:199], v[188:189], off offset:64
	global_load_dwordx4 v[200:203], v[188:189], off offset:512
	global_load_dwordx4 v[204:207], v[188:189], off offset:576
	v_lshl_add_u64 v[190:191], s[58:59], 0, v[176:177]
	s_waitcnt vmcnt(3)
	v_pk_add_f32 v[32:33], v[32:33], v[186:187]
	v_pk_add_f32 v[30:31], v[30:31], v[184:185]
	global_store_dwordx4 v[190:191], v[30:33], off
	v_mul_f32_e32 v176, v31, v31
	v_mul_f32_e32 v177, v33, v33
	v_fmac_f32_e32 v176, v30, v30
	v_fmac_f32_e32 v177, v32, v32
	v_add_f32_e32 v176, v176, v177
	s_waitcnt vmcnt(3)
	v_pk_add_f32 v[28:29], v[28:29], v[198:199]
	v_pk_add_f32 v[26:27], v[26:27], v[196:197]
	global_store_dwordx4 v[190:191], v[26:29], off offset:64
	v_mul_f32_e32 v177, v27, v27
	v_fmac_f32_e32 v177, v26, v26
	s_waitcnt vmcnt(3)
	v_pk_add_f32 v[24:25], v[24:25], v[202:203]
	v_pk_add_f32 v[22:23], v[22:23], v[200:201]
	global_store_dwordx4 v[190:191], v[22:25], off offset:512
	v_mul_f32_e32 v188, v29, v29
	v_fmac_f32_e32 v188, v28, v28
	v_add_f32_e32 v177, v177, v188
	v_add_f32_e32 v176, v176, v177
	v_mul_f32_e32 v177, v23, v23
	v_mul_f32_e32 v188, v25, v25
	v_fmac_f32_e32 v177, v22, v22
	v_fmac_f32_e32 v188, v24, v24
	v_add_f32_e32 v177, v177, v188
	v_add_f32_e32 v176, v176, v177
	s_waitcnt vmcnt(3)
	v_pk_add_f32 v[20:21], v[20:21], v[206:207]
	v_pk_add_f32 v[18:19], v[18:19], v[204:205]
	v_mul_f32_e32 v184, v21, v21
	v_mul_f32_e32 v177, v19, v19
	v_fmac_f32_e32 v177, v18, v18
	v_fmac_f32_e32 v184, v20, v20
	v_add_f32_e32 v177, v177, v184
	v_add_f32_e32 v176, v176, v177
	ds_bpermute_b32 v177, v182, v176
	global_store_dwordx4 v[190:191], v[18:21], off offset:576
	s_waitcnt lgkmcnt(0)
	v_add_f32_e32 v176, v176, v177
	ds_bpermute_b32 v177, v183, v176
	s_and_saveexec_b64 s[0:1], s[4:5]
	s_cbranch_execz .LBB0_927
	v_lshl_add_u64 v[184:185], v[174:175], 2, s[16:17]
	s_waitcnt lgkmcnt(0)
	v_add_f32_e32 v176, v176, v177
	global_atomic_add_f32 v[184:185], v176, off
.LBB0_927:
	s_or_b64 exec, exec, s[0:1]
	v_add_u32_e32 v176, 0xb0, v154
	s_waitcnt lgkmcnt(0)
	v_ashrrev_i32_e32 v177, 31, v176
	v_lshlrev_b64 v[184:185], 11, v[176:177]
	v_lshl_add_u64 v[184:185], v[184:185], 0, v[156:157]
	v_lshlrev_b64 v[188:189], 2, v[184:185]
	v_lshl_add_u64 v[190:191], s[14:15], 0, v[188:189]
	global_load_dwordx4 v[184:187], v[190:191], off
	global_load_dwordx4 v[196:199], v[190:191], off offset:64
	global_load_dwordx4 v[200:203], v[190:191], off offset:512
	global_load_dwordx4 v[204:207], v[190:191], off offset:576
	v_lshl_add_u64 v[188:189], s[58:59], 0, v[188:189]
	s_waitcnt vmcnt(3)
	v_pk_add_f32 v[16:17], v[16:17], v[186:187]
	v_pk_add_f32 v[14:15], v[14:15], v[184:185]
	global_store_dwordx4 v[188:189], v[14:17], off
	s_waitcnt vmcnt(3)
	v_pk_add_f32 v[12:13], v[12:13], v[198:199]
	v_pk_add_f32 v[10:11], v[10:11], v[196:197]
	global_store_dwordx4 v[188:189], v[10:13], off offset:64
	v_mul_f32_e32 v192, v13, v13
	v_fmac_f32_e32 v192, v12, v12
	s_waitcnt vmcnt(3)
	v_pk_add_f32 v[8:9], v[8:9], v[202:203]
	v_pk_add_f32 v[6:7], v[6:7], v[200:201]
	global_store_dwordx4 v[188:189], v[6:9], off offset:512
	v_mul_f32_e32 v190, v15, v15
	v_mul_f32_e32 v191, v17, v17
	v_fmac_f32_e32 v190, v14, v14
	v_fmac_f32_e32 v191, v16, v16
	v_add_f32_e32 v190, v190, v191
	v_mul_f32_e32 v191, v11, v11
	v_fmac_f32_e32 v191, v10, v10
	v_add_f32_e32 v191, v191, v192
	v_add_f32_e32 v190, v190, v191
	v_mul_f32_e32 v191, v7, v7
	v_mul_f32_e32 v192, v9, v9
	v_fmac_f32_e32 v191, v6, v6
	v_fmac_f32_e32 v192, v8, v8
	v_add_f32_e32 v191, v191, v192
	v_add_f32_e32 v190, v190, v191
	s_waitcnt vmcnt(3)
	v_pk_add_f32 v[4:5], v[4:5], v[206:207]
	v_pk_add_f32 v[2:3], v[2:3], v[204:205]
	v_mul_f32_e32 v185, v5, v5
	v_mul_f32_e32 v184, v3, v3
	v_fmac_f32_e32 v184, v2, v2
	v_fmac_f32_e32 v185, v4, v4
	v_add_f32_e32 v184, v184, v185
	v_add_f32_e32 v184, v190, v184
	ds_bpermute_b32 v182, v182, v184
	global_store_dwordx4 v[188:189], v[2:5], off offset:576
	s_waitcnt lgkmcnt(0)
	v_add_f32_e32 v182, v184, v182
	ds_bpermute_b32 v183, v183, v182
	s_and_saveexec_b64 s[0:1], s[4:5]
	s_cbranch_execz .LBB0_929
	v_lshl_add_u64 v[184:185], v[176:177], 2, s[16:17]
	s_waitcnt lgkmcnt(0)
	v_add_f32_e32 v182, v182, v183
	global_atomic_add_f32 v[184:185], v182, off

; __device__ __forceinline__ unsigned cvt_pk_bf16(float lo, float hi) { const f32x2e_t v = {lo, hi}; return __builtin_bit_cast(unsigned, __builtin_convertvector(v, bf16x2e_t)); }
;     __device__ __forceinline__ void operator()(f32x4 (&acc)[2][2][4][2], const Unit& u, int wr, int wc, int fr, int fq) const {
;     ...
;         asm volatile("s_waitcnt vmcnt(0) lgkmcnt(0)" ::: "memory");
;         __builtin_amdgcn_s_barrier();
;         asm volatile("" ::: "memory");
;         f32x4 gv[2][2];
;         if (FINAL) {
; #pragma unroll
;             for (int bj = 0; bj < 2; ++bj)
; #pragma unroll
;                 for (int n = 0; n < 2; ++n) gv[bj][n] = *(const f32x4*)(fgain + col0 + bj * HALF + n * 16); }
; #pragma unroll
;         for (int ai = 0; ai < 2; ++ai)
; #pragma unroll
;             for (int m = 0; m < 4; ++m) { const int row = row0 + ai * HALF + m * 16; const size_t off = (size_t)row * 2048 + col0;
;                 const float r = rsqrtf(__hip_atomic_load(ssq + row, __ATOMIC_RELAXED, __HIP_MEMORY_SCOPE_AGENT) * (1.0f / 2048.0f) + 1e-6f);
; #pragma unroll
;                 for (int bj = 0; bj < 2; ++bj)
; #pragma unroll
;                     for (int n = 0; n < 2; ++n) { const f32x4 xo = acc[ai][bj][m][n] * r;
;                         if (FINAL) *(f32x4*)(X + off + bj * HALF + n * 16) = xo * gv[bj][n];
;                         else { unsigned long long w = (unsigned long long)cvt_pk_bf16(xo[0], xo[1]) | ((unsigned long long)cvt_pk_bf16(xo[2], xo[3]) << 32); *(unsigned long long*)(XB + off + bj * HALF + n * 16) = w; } } }
.LBB0_944:
	s_or_b64 exec, exec, s[0:1]
	s_waitcnt vmcnt(0) lgkmcnt(0)
	s_barrier
	global_load_dword v208, v[152:153], off sc1
	global_load_dword v209, v[162:163], off sc1
	global_load_dword v210, v[166:167], off sc1
	global_load_dword v211, v[170:171], off sc1
	global_load_dword v212, v[152:153], off offset:512 sc1
	global_load_dword v213, v[152:153], off offset:576 sc1
	global_load_dword v214, v[152:153], off offset:640 sc1
	global_load_dword v215, v[152:153], off offset:704 sc1
	v_lshl_add_u64 v[156:157], v[156:157], 1, s[44:45]
	v_lshlrev_b64 v[154:155], 12, v[154:155]
	v_lshl_add_u64 v[154:155], v[156:157], 0, v[154:155]
	s_waitcnt vmcnt(0)
	v_fmamk_f32 v182, v208, 0x3a000000, v239
	s_waitcnt lgkmcnt(0)
	v_mul_f32_e32 v183, 0x4b800000, v182
	v_cmp_gt_f32_e32 vcc, s74, v182
	s_nop 1
	v_cndmask_b32_e32 v182, v182, v183, vcc
	v_rsq_f32_e32 v182, v182
	s_nop 0
	v_mul_f32_e32 v183, 0x45800000, v182
	v_cndmask_b32_e32 v182, v182, v183, vcc
	v_pk_mul_f32 v[76:77], v[76:77], v[182:183] op_sel_hi:[1,0]
	v_pk_mul_f32 v[74:75], v[74:75], v[182:183] op_sel_hi:[1,0]
	v_pk_mul_f32 v[80:81], v[80:81], v[182:183] op_sel_hi:[1,0]
	v_pk_mul_f32 v[78:79], v[78:79], v[182:183] op_sel_hi:[1,0]
	v_pk_mul_f32 v[84:85], v[84:85], v[182:183] op_sel_hi:[1,0]
	v_pk_mul_f32 v[82:83], v[82:83], v[182:183] op_sel_hi:[1,0]
	v_pk_mul_f32 v[96:97], v[96:97], v[182:183] op_sel_hi:[1,0]
	v_pk_mul_f32 v[94:95], v[94:95], v[182:183] op_sel_hi:[1,0]
	v_cvt_pk_bf16_f32 v74, v74, v75
	v_cvt_pk_bf16_f32 v75, v76, v77
	v_cvt_pk_bf16_f32 v76, v78, v79
	v_cvt_pk_bf16_f32 v77, v80, v81
	v_cvt_pk_bf16_f32 v78, v82, v83
	v_cvt_pk_bf16_f32 v79, v84, v85
	v_cvt_pk_bf16_f32 v80, v94, v95
	v_cvt_pk_bf16_f32 v81, v96, v97
	global_store_dwordx2 v[154:155], v[74:75], off
	global_store_dwordx2 v[154:155], v[76:77], off offset:32
	global_store_dwordx2 v[154:155], v[78:79], off offset:256
	global_store_dwordx2 v[154:155], v[80:81], off offset:288
	v_fmamk_f32 v74, v209, 0x3a000000, v239
	v_mul_f32_e32 v75, 0x4b800000, v74
	v_cmp_gt_f32_e32 vcc, s74, v74
	s_nop 1
	v_cndmask_b32_e32 v74, v74, v75, vcc
	v_rsq_f32_e32 v76, v74
	v_lshlrev_b64 v[74:75], 12, v[158:159]
	v_lshl_add_u64 v[74:75], v[156:157], 0, v[74:75]
	v_mul_f32_e32 v77, 0x45800000, v76
	v_cndmask_b32_e32 v76, v76, v77, vcc
	v_pk_mul_f32 v[78:79], v[104:105], v[76:77] op_sel_hi:[1,0]
	v_pk_mul_f32 v[80:81], v[102:103], v[76:77] op_sel_hi:[1,0]
	v_pk_mul_f32 v[82:83], v[108:109], v[76:77] op_sel_hi:[1,0]
	v_pk_mul_f32 v[84:85], v[106:107], v[76:77] op_sel_hi:[1,0]
	v_pk_mul_f32 v[94:95], v[112:113], v[76:77] op_sel_hi:[1,0]
	v_pk_mul_f32 v[96:97], v[110:111], v[76:77] op_sel_hi:[1,0]
	v_pk_mul_f32 v[102:103], v[120:121], v[76:77] op_sel_hi:[1,0]
	v_pk_mul_f32 v[76:77], v[118:119], v[76:77] op_sel_hi:[1,0]
	v_cvt_pk_bf16_f32 v80, v80, v81
	v_cvt_pk_bf16_f32 v81, v78, v79
	v_cvt_pk_bf16_f32 v78, v84, v85
	v_cvt_pk_bf16_f32 v79, v82, v83
	v_cvt_pk_bf16_f32 v82, v96, v97
	v_cvt_pk_bf16_f32 v83, v94, v95
	v_cvt_pk_bf16_f32 v76, v76, v77
	v_cvt_pk_bf16_f32 v77, v102, v103
	global_store_dwordx2 v[74:75], v[80:81], off
	global_store_dwordx2 v[74:75], v[78:79], off offset:32
	global_store_dwordx2 v[74:75], v[82:83], off offset:256
	global_store_dwordx2 v[74:75], v[76:77], off offset:288
	v_fmamk_f32 v74, v210, 0x3a000000, v239
	v_mul_f32_e32 v75, 0x4b800000, v74
	v_cmp_gt_f32_e32 vcc, s74, v74
	s_nop 1
	v_cndmask_b32_e32 v74, v74, v75, vcc
	v_rsq_f32_e32 v76, v74
	v_lshlrev_b64 v[74:75], 12, v[160:161]
	v_lshl_add_u64 v[74:75], v[156:157], 0, v[74:75]
	v_mul_f32_e32 v77, 0x45800000, v76
	v_cndmask_b32_e32 v76, v76, v77, vcc
	v_pk_mul_f32 v[78:79], v[124:125], v[76:77] op_sel_hi:[1,0]
	v_pk_mul_f32 v[80:81], v[122:123], v[76:77] op_sel_hi:[1,0]
	v_pk_mul_f32 v[82:83], v[146:147], v[76:77] op_sel_hi:[1,0]
	v_pk_mul_f32 v[84:85], v[144:145], v[76:77] op_sel_hi:[1,0]
	v_pk_mul_f32 v[94:95], v[116:117], v[76:77] op_sel_hi:[1,0]
	v_pk_mul_f32 v[96:97], v[114:115], v[76:77] op_sel_hi:[1,0]
	v_pk_mul_f32 v[100:101], v[100:101], v[76:77] op_sel_hi:[1,0]
	v_pk_mul_f32 v[76:77], v[98:99], v[76:77] op_sel_hi:[1,0]
	v_cvt_pk_bf16_f32 v80, v80, v81
	v_cvt_pk_bf16_f32 v81, v78, v79
	v_cvt_pk_bf16_f32 v78, v84, v85
	v_cvt_pk_bf16_f32 v79, v82, v83
	v_cvt_pk_bf16_f32 v82, v96, v97
	v_cvt_pk_bf16_f32 v83, v94, v95
	v_cvt_pk_bf16_f32 v76, v76, v77
	v_cvt_pk_bf16_f32 v77, v100, v101
	global_store_dwordx2 v[74:75], v[80:81], off
	global_store_dwordx2 v[74:75], v[78:79], off offset:32
	global_store_dwordx2 v[74:75], v[82:83], off offset:256
	global_store_dwordx2 v[74:75], v[76:77], off offset:288
	v_fmamk_f32 v74, v211, 0x3a000000, v239
	v_mul_f32_e32 v75, 0x4b800000, v74
	v_cmp_gt_f32_e32 vcc, s74, v74
	s_nop 1
	v_cndmask_b32_e32 v74, v74, v75, vcc
	v_rsq_f32_e32 v76, v74
	v_lshlrev_b64 v[74:75], 12, v[164:165]
	v_lshl_add_u64 v[74:75], v[156:157], 0, v[74:75]
	v_mul_f32_e32 v77, 0x45800000, v76
	v_cndmask_b32_e32 v76, v76, v77, vcc
	v_pk_mul_f32 v[78:79], v[92:93], v[76:77] op_sel_hi:[1,0]
	v_pk_mul_f32 v[80:81], v[90:91], v[76:77] op_sel_hi:[1,0]
	v_pk_mul_f32 v[82:83], v[88:89], v[76:77] op_sel_hi:[1,0]
	v_pk_mul_f32 v[84:85], v[86:87], v[76:77] op_sel_hi:[1,0]
	v_pk_mul_f32 v[72:73], v[72:73], v[76:77] op_sel_hi:[1,0]
	v_pk_mul_f32 v[70:71], v[70:71], v[76:77] op_sel_hi:[1,0]
	v_pk_mul_f32 v[68:69], v[68:69], v[76:77] op_sel_hi:[1,0]
	v_pk_mul_f32 v[66:67], v[66:67], v[76:77] op_sel_hi:[1,0]
	v_cvt_pk_bf16_f32 v76, v80, v81
	v_cvt_pk_bf16_f32 v77, v78, v79
	v_cvt_pk_bf16_f32 v78, v84, v85
	v_cvt_pk_bf16_f32 v79, v82, v83
	v_cvt_pk_bf16_f32 v70, v70, v71
	v_cvt_pk_bf16_f32 v71, v72, v73
	v_cvt_pk_bf16_f32 v66, v66, v67
; __device__ __forceinline__ unsigned cvt_pk_bf16(float lo, float hi) { const f32x2e_t v = {lo, hi}; return __builtin_bit_cast(unsigned, __builtin_convertvector(v, bf16x2e_t)); }
;     __device__ __forceinline__ void operator()(f32x4 (&acc)[2][2][4][2], const Unit& u, int wr, int wc, int fr, int fq) const {
;     ...
;         for (int ai = 0; ai < 2; ++ai)
; #pragma unroll
;             for (int m = 0; m < 4; ++m) { const int row = row0 + ai * HALF + m * 16; const size_t off = (size_t)row * 2048 + col0;
;                 const float r = rsqrtf(__hip_atomic_load(ssq + row, __ATOMIC_RELAXED, __HIP_MEMORY_SCOPE_AGENT) * (1.0f / 2048.0f) + 1e-6f);
; #pragma unroll
;                 for (int bj = 0; bj < 2; ++bj)
; #pragma unroll
;                     for (int n = 0; n < 2; ++n) { const f32x4 xo = acc[ai][bj][m][n] * r;
;                         if (FINAL) *(f32x4*)(X + off + bj * HALF + n * 16) = xo * gv[bj][n];
;                         else { unsigned long long w = (unsigned long long)cvt_pk_bf16(xo[0], xo[1]) | ((unsigned long long)cvt_pk_bf16(xo[2], xo[3]) << 32); *(unsigned long long*)(XB + off + bj * HALF + n * 16) = w; } } }
	v_cvt_pk_bf16_f32 v67, v68, v69
	global_store_dwordx2 v[74:75], v[76:77], off
	global_store_dwordx2 v[74:75], v[78:79], off offset:32
	global_store_dwordx2 v[74:75], v[70:71], off offset:256
	global_store_dwordx2 v[74:75], v[66:67], off offset:288
	v_fmamk_f32 v66, v212, 0x3a000000, v239
	v_mul_f32_e32 v67, 0x4b800000, v66
	v_cmp_gt_f32_e32 vcc, s74, v66
	s_nop 1
	v_cndmask_b32_e32 v66, v66, v67, vcc
	v_rsq_f32_e32 v68, v66
	v_lshlrev_b64 v[66:67], 12, v[168:169]
	v_lshl_add_u64 v[66:67], v[156:157], 0, v[66:67]
	v_mul_f32_e32 v69, 0x45800000, v68
	v_cndmask_b32_e32 v68, v68, v69, vcc
	v_pk_mul_f32 v[64:65], v[64:65], v[68:69] op_sel_hi:[1,0]
	v_pk_mul_f32 v[62:63], v[62:63], v[68:69] op_sel_hi:[1,0]
	v_pk_mul_f32 v[60:61], v[60:61], v[68:69] op_sel_hi:[1,0]
	v_pk_mul_f32 v[58:59], v[58:59], v[68:69] op_sel_hi:[1,0]
	v_pk_mul_f32 v[56:57], v[56:57], v[68:69] op_sel_hi:[1,0]
	v_pk_mul_f32 v[54:55], v[54:55], v[68:69] op_sel_hi:[1,0]
	v_pk_mul_f32 v[52:53], v[52:53], v[68:69] op_sel_hi:[1,0]
	v_pk_mul_f32 v[50:51], v[50:51], v[68:69] op_sel_hi:[1,0]
	v_cvt_pk_bf16_f32 v62, v62, v63
	v_cvt_pk_bf16_f32 v63, v64, v65
	v_cvt_pk_bf16_f32 v58, v58, v59
	v_cvt_pk_bf16_f32 v59, v60, v61
	v_cvt_pk_bf16_f32 v54, v54, v55
	v_cvt_pk_bf16_f32 v55, v56, v57
	v_cvt_pk_bf16_f32 v50, v50, v51
	v_cvt_pk_bf16_f32 v51, v52, v53
	global_store_dwordx2 v[66:67], v[62:63], off
	global_store_dwordx2 v[66:67], v[58:59], off offset:32
	global_store_dwordx2 v[66:67], v[54:55], off offset:256
	global_store_dwordx2 v[66:67], v[50:51], off offset:288
	v_fmamk_f32 v50, v213, 0x3a000000, v239
	v_mul_f32_e32 v51, 0x4b800000, v50
	v_cmp_gt_f32_e32 vcc, s74, v50
	s_nop 1
	v_cndmask_b32_e32 v50, v50, v51, vcc
	v_rsq_f32_e32 v52, v50
	v_lshlrev_b64 v[50:51], 12, v[172:173]
	v_lshl_add_u64 v[50:51], v[156:157], 0, v[50:51]
	v_mul_f32_e32 v53, 0x45800000, v52
	v_cndmask_b32_e32 v52, v52, v53, vcc
	v_pk_mul_f32 v[48:49], v[48:49], v[52:53] op_sel_hi:[1,0]
	v_pk_mul_f32 v[46:47], v[46:47], v[52:53] op_sel_hi:[1,0]
	v_pk_mul_f32 v[44:45], v[44:45], v[52:53] op_sel_hi:[1,0]
	v_pk_mul_f32 v[42:43], v[42:43], v[52:53] op_sel_hi:[1,0]
	v_pk_mul_f32 v[40:41], v[40:41], v[52:53] op_sel_hi:[1,0]
	v_pk_mul_f32 v[38:39], v[38:39], v[52:53] op_sel_hi:[1,0]
	v_pk_mul_f32 v[36:37], v[36:37], v[52:53] op_sel_hi:[1,0]
	v_pk_mul_f32 v[34:35], v[34:35], v[52:53] op_sel_hi:[1,0]
	v_cvt_pk_bf16_f32 v46, v46, v47
	v_cvt_pk_bf16_f32 v47, v48, v49
	v_cvt_pk_bf16_f32 v42, v42, v43
	v_cvt_pk_bf16_f32 v43, v44, v45
	v_cvt_pk_bf16_f32 v38, v38, v39
	v_cvt_pk_bf16_f32 v39, v40, v41
	v_cvt_pk_bf16_f32 v34, v34, v35
	v_cvt_pk_bf16_f32 v35, v36, v37
	global_store_dwordx2 v[50:51], v[46:47], off
	global_store_dwordx2 v[50:51], v[42:43], off offset:32
	global_store_dwordx2 v[50:51], v[38:39], off offset:256
	global_store_dwordx2 v[50:51], v[34:35], off offset:288
	v_fmamk_f32 v34, v214, 0x3a000000, v239
	v_mul_f32_e32 v35, 0x4b800000, v34
	v_cmp_gt_f32_e32 vcc, s74, v34
	s_nop 1
	v_cndmask_b32_e32 v34, v34, v35, vcc
	v_rsq_f32_e32 v36, v34
	v_lshlrev_b64 v[34:35], 12, v[174:175]
	v_lshl_add_u64 v[34:35], v[156:157], 0, v[34:35]
	v_mul_f32_e32 v37, 0x45800000, v36
	v_cndmask_b32_e32 v36, v36, v37, vcc
	v_pk_mul_f32 v[32:33], v[32:33], v[36:37] op_sel_hi:[1,0]
	v_pk_mul_f32 v[30:31], v[30:31], v[36:37] op_sel_hi:[1,0]
	v_pk_mul_f32 v[28:29], v[28:29], v[36:37] op_sel_hi:[1,0]
	v_pk_mul_f32 v[26:27], v[26:27], v[36:37] op_sel_hi:[1,0]
	v_pk_mul_f32 v[24:25], v[24:25], v[36:37] op_sel_hi:[1,0]
	v_pk_mul_f32 v[22:23], v[22:23], v[36:37] op_sel_hi:[1,0]
	v_pk_mul_f32 v[20:21], v[20:21], v[36:37] op_sel_hi:[1,0]
	v_pk_mul_f32 v[18:19], v[18:19], v[36:37] op_sel_hi:[1,0]
	v_cvt_pk_bf16_f32 v30, v30, v31
	v_cvt_pk_bf16_f32 v31, v32, v33
	v_cvt_pk_bf16_f32 v26, v26, v27
	v_cvt_pk_bf16_f32 v27, v28, v29
	v_cvt_pk_bf16_f32 v22, v22, v23
	v_cvt_pk_bf16_f32 v23, v24, v25
	v_cvt_pk_bf16_f32 v18, v18, v19
	v_cvt_pk_bf16_f32 v19, v20, v21
	global_store_dwordx2 v[34:35], v[30:31], off
	global_store_dwordx2 v[34:35], v[26:27], off offset:32
	global_store_dwordx2 v[34:35], v[22:23], off offset:256
	global_store_dwordx2 v[34:35], v[18:19], off offset:288
	v_lshlrev_b64 v[18:19], 12, v[176:177]
	v_lshl_add_u64 v[18:19], v[156:157], 0, v[18:19]
	s_andn2_b64 vcc, exec, s[6:7]
	v_fmamk_f32 v20, v215, 0x3a000000, v239
	v_mul_f32_e32 v21, 0x4b800000, v20
	v_cmp_gt_f32_e64 s[0:1], s74, v20
	s_nop 1
	v_cndmask_b32_e64 v20, v20, v21, s[0:1]
	v_rsq_f32_e32 v20, v20
	s_nop 0
	v_mul_f32_e32 v21, 0x45800000, v20
	v_cndmask_b32_e64 v20, v20, v21, s[0:1]
	v_pk_mul_f32 v[16:17], v[16:17], v[20:21] op_sel_hi:[1,0]
	v_pk_mul_f32 v[14:15], v[14:15], v[20:21] op_sel_hi:[1,0]
	v_pk_mul_f32 v[12:13], v[12:13], v[20:21] op_sel_hi:[1,0]
	v_pk_mul_f32 v[10:11], v[10:11], v[20:21] op_sel_hi:[1,0]
	v_pk_mul_f32 v[8:9], v[8:9], v[20:21] op_sel_hi:[1,0]
	v_pk_mul_f32 v[6:7], v[6:7], v[20:21] op_sel_hi:[1,0]
	v_pk_mul_f32 v[4:5], v[4:5], v[20:21] op_sel_hi:[1,0]
	v_pk_mul_f32 v[2:3], v[2:3], v[20:21] op_sel_hi:[1,0]
	v_cvt_pk_bf16_f32 v14, v14, v15
	v_cvt_pk_bf16_f32 v15, v16, v17
	s_mov_b64 s[0:1], -1
	v_cvt_pk_bf16_f32 v10, v10, v11
	v_cvt_pk_bf16_f32 v11, v12, v13
	v_cvt_pk_bf16_f32 v6, v6, v7
	v_cvt_pk_bf16_f32 v7, v8, v9
	v_cvt_pk_bf16_f32 v2, v2, v3
	v_cvt_pk_bf16_f32 v3, v4, v5
	global_store_dwordx2 v[18:19], v[14:15], off
	global_store_dwordx2 v[18:19], v[10:11], off offset:32
	global_store_dwordx2 v[18:19], v[6:7], off offset:256
	global_store_dwordx2 v[18:19], v[2:3], off offset:288
	s_cbranch_vccnz .LBB0_902
	s_andn2_b64 vcc, exec, s[8:9]
	s_cbranch_vccnz .LBB0_901
	s_barrier
	s_branch .LBB0_901

;     __device__ __forceinline__ void operator()(f32x4 (&acc)[2][2][4][2], const Unit& u, int wr, int wc, int fr, int fq) const {
;     ...
;             for (int m = 0; m < 4; ++m) { const int row = row0 + ai * HALF + m * 16; const size_t off = (size_t)row * 2048 + col0; float ss = 0.f;
; #pragma unroll
;                 for (int bj = 0; bj < 2; ++bj)
; #pragma unroll
;                     for (int n = 0; n < 2; ++n) { const f32x4 xo = *(const f32x4*)(Xin + off + bj * HALF + n * 16) + acc[ai][bj][m][n]; acc[ai][bj][m][n] = xo;
;                         if (!FINAL) *(f32x4*)(X + off + bj * HALF + n * 16) = xo;
;                         ss += (xo[0] * xo[0] + xo[1] * xo[1]) + (xo[2] * xo[2] + xo[3] * xo[3]); }
;                 ss += __shfl_xor(ss, 16); ss += __shfl_xor(ss, 32);
;                 if (fq == 0) atomicAdd(ssq + row, ss); }
.LBB0_966:
	v_and_b32_e32 v153, 64, v241
	v_xor_b32_e32 v152, 16, v241
	v_add_u32_e32 v153, 64, v153
	v_cmp_lt_i32_e32 vcc, v152, v153
	v_lshl_add_u32 v162, s28, 8, v196
	v_ashrrev_i32_e32 v163, 31, v162
	v_cndmask_b32_e32 v152, v241, v152, vcc
	v_lshlrev_b32_e32 v200, 2, v152
	v_xor_b32_e32 v152, 32, v241
	v_cmp_lt_i32_e32 vcc, v152, v153
	v_lshl_or_b32 v154, s12, 8, v198
	v_ashrrev_i32_e32 v155, 31, v154
	v_cndmask_b32_e32 v152, v241, v152, vcc
	v_lshlrev_b32_e32 v201, 2, v152
	v_lshlrev_b64 v[152:153], 13, v[162:163]
	v_lshl_add_u64 v[152:153], s[58:59], 0, v[152:153]
	v_lshl_add_u64 v[152:153], v[154:155], 2, v[152:153]
	global_load_dwordx4 v[156:159], v[152:153], off
	global_load_dwordx4 v[204:207], v[152:153], off offset:64
	global_load_dwordx4 v[208:211], v[152:153], off offset:512
	global_load_dwordx4 v[212:215], v[152:153], off offset:576
	v_readlane_b32 s0, v253, 30
	v_readlane_b32 s1, v253, 31
	s_waitcnt vmcnt(3)
	v_pk_add_f32 v[146:147], v[146:147], v[158:159]
	v_pk_add_f32 v[144:145], v[144:145], v[156:157]
	v_mul_f32_e32 v157, v147, v147
	v_mul_f32_e32 v156, v145, v145
	v_fmac_f32_e32 v156, v144, v144
	v_fmac_f32_e32 v157, v146, v146
	v_add_f32_e32 v160, v156, v157
	s_waitcnt vmcnt(2)
	v_pk_add_f32 v[124:125], v[124:125], v[206:207]
	v_pk_add_f32 v[122:123], v[122:123], v[204:205]
	v_mul_f32_e32 v157, v125, v125
	v_mul_f32_e32 v156, v123, v123
	v_fmac_f32_e32 v156, v122, v122
	v_fmac_f32_e32 v157, v124, v124
	v_add_f32_e32 v156, v156, v157
	v_add_f32_e32 v160, v160, v156
	s_waitcnt vmcnt(1)
	v_pk_add_f32 v[120:121], v[120:121], v[210:211]
	v_pk_add_f32 v[118:119], v[118:119], v[208:209]
	v_mul_f32_e32 v157, v121, v121
	v_mul_f32_e32 v156, v119, v119
	v_fmac_f32_e32 v156, v118, v118
	v_fmac_f32_e32 v157, v120, v120
	v_add_f32_e32 v156, v156, v157
	v_add_f32_e32 v160, v160, v156
	s_waitcnt vmcnt(0)
	v_pk_add_f32 v[116:117], v[116:117], v[214:215]
	v_pk_add_f32 v[156:157], v[114:115], v[212:213]
	v_mul_f32_e32 v115, v117, v117
	v_mul_f32_e32 v114, v157, v157
	v_fmac_f32_e32 v114, v156, v156
	v_fmac_f32_e32 v115, v116, v116
	v_add_f32_e32 v114, v114, v115
	v_add_f32_e32 v114, v160, v114
	ds_bpermute_b32 v115, v200, v114
	s_waitcnt lgkmcnt(0)
	v_add_f32_e32 v158, v114, v115
	ds_bpermute_b32 v159, v201, v158
	v_lshl_add_u64 v[114:115], v[162:163], 2, s[0:1]
	s_and_saveexec_b64 s[0:1], s[4:5]
	s_cbranch_execz .LBB0_968
	s_waitcnt lgkmcnt(0)
	v_add_f32_e32 v158, v158, v159
	global_atomic_add_f32 v[114:115], v158, off
.LBB0_968:
	s_or_b64 exec, exec, s[0:1]
	v_or_b32_e32 v160, 16, v162
	v_ashrrev_i32_e32 v161, 31, v160
	s_waitcnt lgkmcnt(0)
	v_lshlrev_b64 v[158:159], 13, v[160:161]
	v_lshl_add_u64 v[158:159], s[58:59], 0, v[158:159]
	v_lshl_add_u64 v[158:159], v[154:155], 2, v[158:159]
	global_load_dwordx4 v[164:167], v[158:159], off
	global_load_dwordx4 v[204:207], v[158:159], off offset:64
	global_load_dwordx4 v[208:211], v[158:159], off offset:512
	global_load_dwordx4 v[212:215], v[158:159], off offset:576
	v_readlane_b32 s0, v253, 30
	v_readlane_b32 s1, v253, 31
	s_waitcnt vmcnt(3)
	v_pk_add_f32 v[112:113], v[112:113], v[166:167]
	v_pk_add_f32 v[110:111], v[110:111], v[164:165]
	v_mul_f32_e32 v164, v113, v113
	v_mul_f32_e32 v163, v111, v111
	v_fmac_f32_e32 v163, v110, v110
	v_fmac_f32_e32 v164, v112, v112
	v_add_f32_e32 v163, v163, v164
	s_waitcnt vmcnt(2)
	v_pk_add_f32 v[108:109], v[108:109], v[206:207]
	v_pk_add_f32 v[106:107], v[106:107], v[204:205]
	v_mul_f32_e32 v165, v109, v109
	v_mul_f32_e32 v164, v107, v107
	v_fmac_f32_e32 v164, v106, v106
	v_fmac_f32_e32 v165, v108, v108
	v_add_f32_e32 v164, v164, v165
	v_add_f32_e32 v163, v163, v164
	s_waitcnt vmcnt(1)
	v_pk_add_f32 v[104:105], v[104:105], v[210:211]
	v_pk_add_f32 v[102:103], v[102:103], v[208:209]
	v_mul_f32_e32 v165, v105, v105
	v_mul_f32_e32 v164, v103, v103
	v_fmac_f32_e32 v164, v102, v102
	v_fmac_f32_e32 v165, v104, v104
	v_add_f32_e32 v164, v164, v165
	v_add_f32_e32 v163, v163, v164
	s_waitcnt vmcnt(0)
	v_pk_add_f32 v[100:101], v[100:101], v[214:215]
	v_pk_add_f32 v[98:99], v[98:99], v[212:213]
	v_mul_f32_e32 v165, v101, v101
	v_mul_f32_e32 v164, v99, v99
	v_fmac_f32_e32 v164, v98, v98
	v_fmac_f32_e32 v165, v100, v100
	v_add_f32_e32 v164, v164, v165
	v_add_f32_e32 v163, v163, v164
	ds_bpermute_b32 v164, v200, v163
	s_waitcnt lgkmcnt(0)
	v_add_f32_e32 v163, v163, v164
	ds_bpermute_b32 v166, v201, v163
	v_lshl_add_u64 v[164:165], v[160:161], 2, s[0:1]
	s_and_saveexec_b64 s[0:1], s[4:5]
	s_cbranch_execz .LBB0_970
	s_waitcnt lgkmcnt(0)
	v_add_f32_e32 v160, v163, v166
	global_atomic_add_f32 v[164:165], v160, off
.LBB0_970:
	s_or_b64 exec, exec, s[0:1]
	s_waitcnt lgkmcnt(0)
	v_or_b32_e32 v166, 32, v162
	v_ashrrev_i32_e32 v167, 31, v166
	v_lshlrev_b64 v[160:161], 13, v[166:167]
	v_lshl_add_u64 v[160:161], s[58:59], 0, v[160:161]
	v_lshl_add_u64 v[160:161], v[154:155], 2, v[160:161]
	global_load_dwordx4 v[168:171], v[160:161], off
	global_load_dwordx4 v[204:207], v[160:161], off offset:64
	global_load_dwordx4 v[208:211], v[160:161], off offset:512
	global_load_dwordx4 v[212:215], v[160:161], off offset:576
	v_readlane_b32 s0, v253, 30
	v_readlane_b32 s1, v253, 31
	s_waitcnt vmcnt(3)
	v_pk_add_f32 v[96:97], v[96:97], v[170:171]
	v_pk_add_f32 v[94:95], v[94:95], v[168:169]
	v_mul_f32_e32 v168, v97, v97
	v_mul_f32_e32 v163, v95, v95
	v_fmac_f32_e32 v163, v94, v94
	v_fmac_f32_e32 v168, v96, v96
	v_add_f32_e32 v163, v163, v168
	s_waitcnt vmcnt(2)
	v_pk_add_f32 v[92:93], v[92:93], v[206:207]
	v_pk_add_f32 v[90:91], v[90:91], v[204:205]
	v_mul_f32_e32 v169, v93, v93
	v_mul_f32_e32 v168, v91, v91
	v_fmac_f32_e32 v168, v90, v90
	v_fmac_f32_e32 v169, v92, v92
	v_add_f32_e32 v168, v168, v169
	v_add_f32_e32 v163, v163, v168
	s_waitcnt vmcnt(1)
	v_pk_add_f32 v[88:89], v[88:89], v[210:211]
	v_pk_add_f32 v[86:87], v[86:87], v[208:209]
	v_mul_f32_e32 v169, v89, v89
	v_mul_f32_e32 v168, v87, v87
	v_fmac_f32_e32 v168, v86, v86
	v_fmac_f32_e32 v169, v88, v88
	v_add_f32_e32 v168, v168, v169
	v_add_f32_e32 v163, v163, v168
	s_waitcnt vmcnt(0)
	v_pk_add_f32 v[84:85], v[84:85], v[214:215]
	v_pk_add_f32 v[82:83], v[82:83], v[212:213]
	v_mul_f32_e32 v169, v85, v85
	v_mul_f32_e32 v168, v83, v83
	v_fmac_f32_e32 v168, v82, v82
	v_fmac_f32_e32 v169, v84, v84
	v_add_f32_e32 v168, v168, v169
	v_add_f32_e32 v163, v163, v168
	ds_bpermute_b32 v168, v200, v163
	s_waitcnt lgkmcnt(0)
	v_add_f32_e32 v163, v163, v168
	ds_bpermute_b32 v170, v201, v163
	v_lshl_add_u64 v[168:169], v[166:167], 2, s[0:1]
	s_and_saveexec_b64 s[0:1], s[4:5]
	s_cbranch_execz .LBB0_972
	s_waitcnt lgkmcnt(0)
	v_add_f32_e32 v163, v163, v170
	global_atomic_add_f32 v[168:169], v163, off
;     __device__ __forceinline__ void operator()(f32x4 (&acc)[2][2][4][2], const Unit& u, int wr, int wc, int fr, int fq) const {
;     ...
;             for (int m = 0; m < 4; ++m) { const int row = row0 + ai * HALF + m * 16; const size_t off = (size_t)row * 2048 + col0; float ss = 0.f;
; #pragma unroll
;                 for (int bj = 0; bj < 2; ++bj)
; #pragma unroll
;                     for (int n = 0; n < 2; ++n) { const f32x4 xo = *(const f32x4*)(Xin + off + bj * HALF + n * 16) + acc[ai][bj][m][n]; acc[ai][bj][m][n] = xo;
;                         if (!FINAL) *(f32x4*)(X + off + bj * HALF + n * 16) = xo;
;                         ss += (xo[0] * xo[0] + xo[1] * xo[1]) + (xo[2] * xo[2] + xo[3] * xo[3]); }
;                 ss += __shfl_xor(ss, 16); ss += __shfl_xor(ss, 32);
;                 if (fq == 0) atomicAdd(ssq + row, ss); }
.LBB0_972:
	s_or_b64 exec, exec, s[0:1]
	s_waitcnt lgkmcnt(0)
	v_or_b32_e32 v170, 48, v162
	v_ashrrev_i32_e32 v171, 31, v170
	v_lshlrev_b64 v[166:167], 13, v[170:171]
	v_lshl_add_u64 v[166:167], s[58:59], 0, v[166:167]
	v_lshl_add_u64 v[166:167], v[154:155], 2, v[166:167]
	global_load_dwordx4 v[172:175], v[166:167], off
	global_load_dwordx4 v[204:207], v[166:167], off offset:64
	global_load_dwordx4 v[208:211], v[166:167], off offset:512
	global_load_dwordx4 v[212:215], v[166:167], off offset:576
	v_readlane_b32 s0, v253, 30
	v_readlane_b32 s1, v253, 31
	s_waitcnt vmcnt(3)
	v_pk_add_f32 v[80:81], v[80:81], v[174:175]
	v_pk_add_f32 v[78:79], v[78:79], v[172:173]
	v_mul_f32_e32 v172, v81, v81
	v_mul_f32_e32 v163, v79, v79
	v_fmac_f32_e32 v163, v78, v78
	v_fmac_f32_e32 v172, v80, v80
	v_add_f32_e32 v163, v163, v172
	s_waitcnt vmcnt(2)
	v_pk_add_f32 v[76:77], v[76:77], v[206:207]
	v_pk_add_f32 v[74:75], v[74:75], v[204:205]
	v_mul_f32_e32 v173, v77, v77
	v_mul_f32_e32 v172, v75, v75
	v_fmac_f32_e32 v172, v74, v74
	v_fmac_f32_e32 v173, v76, v76
	v_add_f32_e32 v172, v172, v173
	v_add_f32_e32 v163, v163, v172
	s_waitcnt vmcnt(1)
	v_pk_add_f32 v[72:73], v[72:73], v[210:211]
	v_pk_add_f32 v[70:71], v[70:71], v[208:209]
	v_mul_f32_e32 v173, v73, v73
	v_mul_f32_e32 v172, v71, v71
	v_fmac_f32_e32 v172, v70, v70
	v_fmac_f32_e32 v173, v72, v72
	v_add_f32_e32 v172, v172, v173
	v_add_f32_e32 v163, v163, v172
	s_waitcnt vmcnt(0)
	v_pk_add_f32 v[68:69], v[68:69], v[214:215]
	v_pk_add_f32 v[66:67], v[66:67], v[212:213]
	v_mul_f32_e32 v173, v69, v69
	v_mul_f32_e32 v172, v67, v67
	v_fmac_f32_e32 v172, v66, v66
	v_fmac_f32_e32 v173, v68, v68
	v_add_f32_e32 v172, v172, v173
	v_add_f32_e32 v163, v163, v172
	ds_bpermute_b32 v172, v200, v163
	s_waitcnt lgkmcnt(0)
	v_add_f32_e32 v163, v163, v172
	ds_bpermute_b32 v174, v201, v163
	v_lshl_add_u64 v[172:173], v[170:171], 2, s[0:1]
	s_and_saveexec_b64 s[0:1], s[4:5]
	s_cbranch_execz .LBB0_974
	s_waitcnt lgkmcnt(0)
	v_add_f32_e32 v163, v163, v174
	global_atomic_add_f32 v[172:173], v163, off
.LBB0_974:
	s_or_b64 exec, exec, s[0:1]
	s_waitcnt lgkmcnt(0)
	v_add_u32_e32 v174, 0x80, v162
	v_ashrrev_i32_e32 v175, 31, v174
	v_lshlrev_b64 v[170:171], 13, v[174:175]
	v_lshl_add_u64 v[170:171], s[58:59], 0, v[170:171]
	v_lshl_add_u64 v[170:171], v[154:155], 2, v[170:171]
	global_load_dwordx4 v[176:179], v[170:171], off
	global_load_dwordx4 v[204:207], v[170:171], off offset:64
	global_load_dwordx4 v[208:211], v[170:171], off offset:512
	global_load_dwordx4 v[212:215], v[170:171], off offset:576
	s_waitcnt vmcnt(3)
	v_pk_add_f32 v[64:65], v[64:65], v[178:179]
	v_pk_add_f32 v[62:63], v[62:63], v[176:177]
	v_mul_f32_e32 v176, v65, v65
	v_mul_f32_e32 v163, v63, v63
	v_fmac_f32_e32 v163, v62, v62
	v_fmac_f32_e32 v176, v64, v64
	v_add_f32_e32 v163, v163, v176
	s_waitcnt vmcnt(2)
	v_pk_add_f32 v[60:61], v[60:61], v[206:207]
	v_pk_add_f32 v[58:59], v[58:59], v[204:205]
	v_mul_f32_e32 v177, v61, v61
	v_mul_f32_e32 v176, v59, v59
	v_fmac_f32_e32 v176, v58, v58
	v_fmac_f32_e32 v177, v60, v60
	v_add_f32_e32 v176, v176, v177
	v_add_f32_e32 v163, v163, v176
	s_waitcnt vmcnt(1)
	v_pk_add_f32 v[56:57], v[56:57], v[210:211]
	v_pk_add_f32 v[54:55], v[54:55], v[208:209]
	v_mul_f32_e32 v177, v57, v57
	v_mul_f32_e32 v176, v55, v55
	v_fmac_f32_e32 v176, v54, v54
	v_fmac_f32_e32 v177, v56, v56
	v_add_f32_e32 v176, v176, v177
	v_add_f32_e32 v163, v163, v176
	s_waitcnt vmcnt(0)
	v_pk_add_f32 v[52:53], v[52:53], v[214:215]
	v_pk_add_f32 v[50:51], v[50:51], v[212:213]
	v_mul_f32_e32 v177, v53, v53
	v_mul_f32_e32 v176, v51, v51
	v_fmac_f32_e32 v176, v50, v50
	v_fmac_f32_e32 v177, v52, v52
	v_add_f32_e32 v176, v176, v177
	v_add_f32_e32 v163, v163, v176
	ds_bpermute_b32 v176, v200, v163
	s_waitcnt lgkmcnt(0)
	v_add_f32_e32 v163, v163, v176
	ds_bpermute_b32 v176, v201, v163
	s_and_saveexec_b64 s[0:1], s[4:5]
	s_cbranch_execz .LBB0_976
	v_readlane_b32 s12, v253, 30
	v_readlane_b32 s13, v253, 31
	s_waitcnt lgkmcnt(0)
	v_add_f32_e32 v163, v163, v176
	v_lshl_add_u64 v[174:175], v[174:175], 2, s[12:13]
	global_atomic_add_f32 v[174:175], v163, off
;     __device__ __forceinline__ void operator()(f32x4 (&acc)[2][2][4][2], const Unit& u, int wr, int wc, int fr, int fq) const {
;     ...
;             for (int m = 0; m < 4; ++m) { const int row = row0 + ai * HALF + m * 16; const size_t off = (size_t)row * 2048 + col0; float ss = 0.f;
; #pragma unroll
;                 for (int bj = 0; bj < 2; ++bj)
; #pragma unroll
;                     for (int n = 0; n < 2; ++n) { const f32x4 xo = *(const f32x4*)(Xin + off + bj * HALF + n * 16) + acc[ai][bj][m][n]; acc[ai][bj][m][n] = xo;
;                         if (!FINAL) *(f32x4*)(X + off + bj * HALF + n * 16) = xo;
;                         ss += (xo[0] * xo[0] + xo[1] * xo[1]) + (xo[2] * xo[2] + xo[3] * xo[3]); }
;                 ss += __shfl_xor(ss, 16); ss += __shfl_xor(ss, 32);
;                 if (fq == 0) atomicAdd(ssq + row, ss); }
.LBB0_976:
	s_or_b64 exec, exec, s[0:1]
	s_waitcnt lgkmcnt(0)
	v_add_u32_e32 v176, 0x90, v162
	v_ashrrev_i32_e32 v177, 31, v176
	v_lshlrev_b64 v[174:175], 13, v[176:177]
	v_lshl_add_u64 v[174:175], s[58:59], 0, v[174:175]
	v_lshl_add_u64 v[174:175], v[154:155], 2, v[174:175]
	global_load_dwordx4 v[178:181], v[174:175], off
	global_load_dwordx4 v[204:207], v[174:175], off offset:64
	global_load_dwordx4 v[208:211], v[174:175], off offset:512
	global_load_dwordx4 v[212:215], v[174:175], off offset:576
	s_waitcnt vmcnt(3)
	v_pk_add_f32 v[48:49], v[48:49], v[180:181]
	v_pk_add_f32 v[46:47], v[46:47], v[178:179]
	v_mul_f32_e32 v178, v49, v49
	v_mul_f32_e32 v163, v47, v47
	v_fmac_f32_e32 v163, v46, v46
	v_fmac_f32_e32 v178, v48, v48
	v_add_f32_e32 v163, v163, v178
	s_waitcnt vmcnt(2)
	v_pk_add_f32 v[44:45], v[44:45], v[206:207]
	v_pk_add_f32 v[42:43], v[42:43], v[204:205]
	v_mul_f32_e32 v179, v45, v45
	v_mul_f32_e32 v178, v43, v43
	v_fmac_f32_e32 v178, v42, v42
	v_fmac_f32_e32 v179, v44, v44
	v_add_f32_e32 v178, v178, v179
	v_add_f32_e32 v163, v163, v178
	s_waitcnt vmcnt(1)
	v_pk_add_f32 v[40:41], v[40:41], v[210:211]
	v_pk_add_f32 v[38:39], v[38:39], v[208:209]
	v_mul_f32_e32 v179, v41, v41
	v_mul_f32_e32 v178, v39, v39
	v_fmac_f32_e32 v178, v38, v38
	v_fmac_f32_e32 v179, v40, v40
	v_add_f32_e32 v178, v178, v179
	v_add_f32_e32 v163, v163, v178
	s_waitcnt vmcnt(0)
	v_pk_add_f32 v[36:37], v[36:37], v[214:215]
	v_pk_add_f32 v[34:35], v[34:35], v[212:213]
	v_mul_f32_e32 v179, v37, v37
	v_mul_f32_e32 v178, v35, v35
	v_fmac_f32_e32 v178, v34, v34
	v_fmac_f32_e32 v179, v36, v36
	v_add_f32_e32 v178, v178, v179
	v_add_f32_e32 v163, v163, v178
	ds_bpermute_b32 v178, v200, v163
	s_waitcnt lgkmcnt(0)
	v_add_f32_e32 v163, v163, v178
	ds_bpermute_b32 v178, v201, v163
	s_and_saveexec_b64 s[0:1], s[4:5]
	s_cbranch_execz .LBB0_978
	v_readlane_b32 s12, v253, 30
	v_readlane_b32 s13, v253, 31
	s_waitcnt lgkmcnt(0)
	v_add_f32_e32 v163, v163, v178
	v_lshl_add_u64 v[176:177], v[176:177], 2, s[12:13]
	global_atomic_add_f32 v[176:177], v163, off
.LBB0_978:
	s_or_b64 exec, exec, s[0:1]
	s_waitcnt lgkmcnt(0)
	v_add_u32_e32 v178, 0xa0, v162
	v_ashrrev_i32_e32 v179, 31, v178
	v_lshlrev_b64 v[176:177], 13, v[178:179]
	v_lshl_add_u64 v[176:177], s[58:59], 0, v[176:177]
	v_lshl_add_u64 v[176:177], v[154:155], 2, v[176:177]
	global_load_dwordx4 v[180:183], v[176:177], off
	global_load_dwordx4 v[204:207], v[176:177], off offset:64
	global_load_dwordx4 v[208:211], v[176:177], off offset:512
	global_load_dwordx4 v[212:215], v[176:177], off offset:576
	s_waitcnt vmcnt(3)
	v_pk_add_f32 v[32:33], v[32:33], v[182:183]
	v_pk_add_f32 v[30:31], v[30:31], v[180:181]
	v_mul_f32_e32 v180, v33, v33
	v_mul_f32_e32 v163, v31, v31
	v_fmac_f32_e32 v163, v30, v30
	v_fmac_f32_e32 v180, v32, v32
	v_add_f32_e32 v163, v163, v180
	s_waitcnt vmcnt(2)
	v_pk_add_f32 v[28:29], v[28:29], v[206:207]
	v_pk_add_f32 v[26:27], v[26:27], v[204:205]
	v_mul_f32_e32 v181, v29, v29
	v_mul_f32_e32 v180, v27, v27
	v_fmac_f32_e32 v180, v26, v26
	v_fmac_f32_e32 v181, v28, v28
	v_add_f32_e32 v180, v180, v181
	v_add_f32_e32 v163, v163, v180
	s_waitcnt vmcnt(1)
	v_pk_add_f32 v[24:25], v[24:25], v[210:211]
	v_pk_add_f32 v[22:23], v[22:23], v[208:209]
	v_mul_f32_e32 v181, v25, v25
	v_mul_f32_e32 v180, v23, v23
	v_fmac_f32_e32 v180, v22, v22
	v_fmac_f32_e32 v181, v24, v24
	v_add_f32_e32 v180, v180, v181
	v_add_f32_e32 v163, v163, v180
	s_waitcnt vmcnt(0)
	v_pk_add_f32 v[20:21], v[20:21], v[214:215]
	v_pk_add_f32 v[18:19], v[18:19], v[212:213]
	v_mul_f32_e32 v181, v21, v21
	v_mul_f32_e32 v180, v19, v19
	v_fmac_f32_e32 v180, v18, v18
	v_fmac_f32_e32 v181, v20, v20
	v_add_f32_e32 v180, v180, v181
	v_add_f32_e32 v163, v163, v180
	ds_bpermute_b32 v180, v200, v163
	s_waitcnt lgkmcnt(0)
	v_add_f32_e32 v163, v163, v180
	ds_bpermute_b32 v180, v201, v163
	s_and_saveexec_b64 s[0:1], s[4:5]
	s_cbranch_execz .LBB0_980
	v_readlane_b32 s12, v253, 30
	v_readlane_b32 s13, v253, 31
	s_waitcnt lgkmcnt(0)
	v_add_f32_e32 v163, v163, v180
	v_lshl_add_u64 v[178:179], v[178:179], 2, s[12:13]
	global_atomic_add_f32 v[178:179], v163, off
.LBB0_980:
	s_or_b64 exec, exec, s[0:1]
	v_add_u32_e32 v194, 0xb0, v162
	v_ashrrev_i32_e32 v195, 31, v194
	v_lshlrev_b64 v[162:163], 13, v[194:195]
	v_lshl_add_u64 v[162:163], s[58:59], 0, v[162:163]
	v_lshl_add_u64 v[162:163], v[154:155], 2, v[162:163]
	s_waitcnt lgkmcnt(0)
	global_load_dwordx4 v[180:183], v[162:163], off
	global_load_dwordx4 v[204:207], v[162:163], off offset:64
	global_load_dwordx4 v[208:211], v[162:163], off offset:512
	global_load_dwordx4 v[212:215], v[162:163], off offset:576
	s_waitcnt vmcnt(3)
	v_pk_add_f32 v[178:179], v[16:17], v[182:183]
	v_pk_add_f32 v[180:181], v[14:15], v[180:181]
	v_mul_f32_e32 v15, v179, v179
	v_mul_f32_e32 v14, v181, v181
	v_fmac_f32_e32 v14, v180, v180
	v_fmac_f32_e32 v15, v178, v178
	v_add_f32_e32 v186, v14, v15
	s_waitcnt vmcnt(2)
	v_pk_add_f32 v[182:183], v[12:13], v[206:207]
	v_pk_add_f32 v[184:185], v[10:11], v[204:205]
	v_mul_f32_e32 v11, v183, v183
	v_mul_f32_e32 v10, v185, v185
	v_fmac_f32_e32 v10, v184, v184
	v_fmac_f32_e32 v11, v182, v182
	v_add_f32_e32 v10, v10, v11
	v_add_f32_e32 v14, v186, v10
	s_waitcnt vmcnt(1)
	v_pk_add_f32 v[186:187], v[8:9], v[210:211]
	v_pk_add_f32 v[188:189], v[6:7], v[208:209]
	v_mul_f32_e32 v7, v187, v187
	v_mul_f32_e32 v6, v189, v189
	v_fmac_f32_e32 v6, v188, v188
	v_fmac_f32_e32 v7, v186, v186
	v_add_f32_e32 v6, v6, v7
	v_add_f32_e32 v10, v14, v6
	s_waitcnt vmcnt(0)
	v_pk_add_f32 v[190:191], v[4:5], v[214:215]
	v_pk_add_f32 v[192:193], v[2:3], v[212:213]
	v_mul_f32_e32 v3, v191, v191
	v_mul_f32_e32 v2, v193, v193
	v_fmac_f32_e32 v2, v192, v192
	v_fmac_f32_e32 v3, v190, v190
	v_add_f32_e32 v2, v2, v3
	v_add_f32_e32 v2, v10, v2
	ds_bpermute_b32 v3, v200, v2
	s_waitcnt lgkmcnt(0)
	v_add_f32_e32 v2, v2, v3
	ds_bpermute_b32 v3, v201, v2
	s_and_saveexec_b64 s[0:1], s[4:5]
	s_cbranch_execz .LBB0_982
	v_readlane_b32 s12, v253, 30
	v_readlane_b32 s13, v253, 31
	s_waitcnt lgkmcnt(0)
	v_add_f32_e32 v2, v2, v3
	v_lshl_add_u64 v[4:5], v[194:195], 2, s[12:13]
	global_atomic_add_f32 v[4:5], v2, off
